# attention: all first-group PV transpose-reads of both tile halves issued early (second-half load addresses computed earlier); plus K swizzle, global K/V loads, no barrier after slot 5
# speedup vs baseline: 1.0115x; 1.0006x over previous
; #define SBAR() __builtin_amdgcn_sched_barrier(0)
; __device__ __forceinline__ void attn_body(const bf16_t* __restrict__ Qb, const bf16_t* __restrict__ Kh, const bf16_t* __restrict__ Vh,
;                                           bf16_t* __restrict__ Ob, const bf16_t* __restrict__ AGb, int seq, char* lds) {
;     ...
;     SBAR(); qkt(pA0, pA1, K_lds, qr, r32, hi);
;     finishSM(pB0, pB1, alB, l_reg, pa0, pa1, pa2, pa3); SBAR();
;     if (j + 3 < NT) SLOAD(SE, (j + 3) * KVBLK); SBAR();
;     pv_d0(o, vb0 + (int)SHM_V, pa0, pa1, pa2, pa3); partialSM(pA0, pA1, m_reg, mnA, alA);
.LBB0_203:
	v_cndmask_b32_e64 v218, v162, v170, s[0:1]
	v_mul_f32_e32 v219, 0xbe0293ee, v218
	v_fmamk_f32 v80, v80, 0x3e0293ee, v219
	v_fmamk_f32 v81, v81, 0x3e0293ee, v219
	v_fmamk_f32 v82, v82, 0x3e0293ee, v219
	v_fmamk_f32 v83, v83, 0x3e0293ee, v219
	v_fmamk_f32 v84, v84, 0x3e0293ee, v219
	v_fmamk_f32 v85, v85, 0x3e0293ee, v219
	v_fmamk_f32 v86, v86, 0x3e0293ee, v219
	v_fmamk_f32 v87, v87, 0x3e0293ee, v219
	v_fmamk_f32 v88, v88, 0x3e0293ee, v219
	v_fmamk_f32 v89, v89, 0x3e0293ee, v219
	v_fmamk_f32 v90, v90, 0x3e0293ee, v219
	v_fmamk_f32 v91, v91, 0x3e0293ee, v219
	v_fmamk_f32 v92, v92, 0x3e0293ee, v219
	v_fmamk_f32 v93, v93, 0x3e0293ee, v219
	v_fmamk_f32 v94, v94, 0x3e0293ee, v219
	v_fmamk_f32 v95, v95, 0x3e0293ee, v219
	v_exp_f32_e32 v162, v80
	v_exp_f32_e32 v177, v81
	v_exp_f32_e32 v163, v82
	v_exp_f32_e32 v176, v83
	v_exp_f32_e32 v164, v84
	v_exp_f32_e32 v175, v85
	v_exp_f32_e32 v165, v86
	v_exp_f32_e32 v174, v87
	v_exp_f32_e32 v166, v88
	v_exp_f32_e32 v173, v89
	v_exp_f32_e32 v167, v90
	v_exp_f32_e32 v172, v91
	v_exp_f32_e32 v168, v92
	v_exp_f32_e32 v171, v93
	v_exp_f32_e32 v169, v94
	v_exp_f32_e32 v170, v95
	v_fmamk_f32 v228, v64, 0x3e0293ee, v219
	v_fmamk_f32 v229, v65, 0x3e0293ee, v219
	v_fmamk_f32 v230, v66, 0x3e0293ee, v219
	v_fmamk_f32 v231, v67, 0x3e0293ee, v219
	v_fmamk_f32 v232, v68, 0x3e0293ee, v219
	v_fmamk_f32 v221, v69, 0x3e0293ee, v219
	v_fmamk_f32 v222, v70, 0x3e0293ee, v219
	v_fmamk_f32 v223, v71, 0x3e0293ee, v219
	v_fmamk_f32 v224, v72, 0x3e0293ee, v219
	v_fmamk_f32 v225, v73, 0x3e0293ee, v219
	v_fmamk_f32 v226, v74, 0x3e0293ee, v219
	v_fmamk_f32 v227, v75, 0x3e0293ee, v219
	v_fmamk_f32 v220, v76, 0x3e0293ee, v219
	v_fmamk_f32 v233, v77, 0x3e0293ee, v219
	v_fmamk_f32 v234, v78, 0x3e0293ee, v219
	v_fmac_f32_e32 v219, 0x3e0293ee, v79
	s_waitcnt lgkmcnt(0)
	s_barrier
	ds_read_b128 v[64:67], v206 offset:32768
	ds_read_b128 v[68:71], v206 offset:40960
	ds_read_b128 v[236:239], v211 offset:32768
	ds_read_b128 v[240:243], v211 offset:40960
	v_exp_f32_e32 v228, v228
	v_exp_f32_e32 v229, v229
	s_waitcnt lgkmcnt(0)
	v_mfma_f32_32x32x16_bf16 v[80:95], v[64:67], v[118:121], 0
	v_exp_f32_e32 v230, v230
	v_exp_f32_e32 v231, v231
	v_exp_f32_e32 v232, v232
	v_exp_f32_e32 v221, v221
	v_exp_f32_e32 v222, v222
	v_exp_f32_e32 v223, v223
	v_exp_f32_e32 v224, v224
	v_mfma_f32_32x32x16_bf16 v[64:79], v[68:71], v[118:121], 0
	v_exp_f32_e32 v225, v225
	v_exp_f32_e32 v226, v226
	v_exp_f32_e32 v227, v227
	v_exp_f32_e32 v235, v220
	v_exp_f32_e32 v233, v233
	v_exp_f32_e32 v234, v234
	v_mfma_f32_32x32x16_bf16 v[80:95], v[236:239], v[114:117], v[80:95]
	v_mfma_f32_32x32x16_bf16 v[64:79], v[240:243], v[114:117], v[64:79]
	ds_read_b128 v[236:239], v210 offset:32768
	ds_read_b128 v[240:243], v210 offset:40960
	s_waitcnt lgkmcnt(0)
	v_mfma_f32_32x32x16_bf16 v[80:95], v[236:239], v[126:129], v[80:95]
	v_mfma_f32_32x32x16_bf16 v[64:79], v[240:243], v[126:129], v[64:79]
	ds_read_b128 v[236:239], v209 offset:32768
	ds_read_b128 v[240:243], v209 offset:40960
	s_waitcnt lgkmcnt(0)
	v_mfma_f32_32x32x16_bf16 v[80:95], v[236:239], v[122:125], v[80:95]
	v_mfma_f32_32x32x16_bf16 v[64:79], v[240:243], v[122:125], v[64:79]
	ds_read_b128 v[236:239], v208 offset:32768
	ds_read_b128 v[240:243], v208 offset:40960
	s_waitcnt lgkmcnt(0)
	v_mfma_f32_32x32x16_bf16 v[80:95], v[236:239], v[110:113], v[80:95]
	v_mfma_f32_32x32x16_bf16 v[64:79], v[240:243], v[110:113], v[64:79]
	ds_read_b128 v[236:239], v207 offset:32768
	ds_read_b128 v[240:243], v207 offset:40960
	s_waitcnt lgkmcnt(0)
	v_mfma_f32_32x32x16_bf16 v[80:95], v[236:239], v[106:109], v[80:95]
	v_mfma_f32_32x32x16_bf16 v[64:79], v[240:243], v[106:109], v[64:79]
	ds_read_b128 v[236:239], v213 offset:32768
	ds_read_b128 v[240:243], v213 offset:40960
	s_waitcnt lgkmcnt(0)
	v_mfma_f32_32x32x16_bf16 v[80:95], v[236:239], v[102:105], v[80:95]
	v_mfma_f32_32x32x16_bf16 v[64:79], v[240:243], v[102:105], v[64:79]
	ds_read_b128 v[236:239], v212 offset:32768
	ds_read_b128 v[240:243], v212 offset:40960
	s_waitcnt lgkmcnt(0)
	v_mfma_f32_32x32x16_bf16 v[80:95], v[236:239], v[98:101], v[80:95]
	v_exp_f32_e32 v236, v219
	v_add_f32_e32 v219, 0, v162
	v_add_f32_e32 v219, v177, v219
	v_add_f32_e32 v219, v163, v219
	v_add_f32_e32 v219, v176, v219
	v_add_f32_e32 v219, v164, v219
	v_add_f32_e32 v219, v175, v219
	v_add_f32_e32 v219, v165, v219
	v_add_f32_e32 v219, v174, v219
	v_add_f32_e32 v219, v166, v219
	v_add_f32_e32 v219, v173, v219
	v_add_f32_e32 v219, v167, v219
	v_add_f32_e32 v219, v172, v219
	v_add_f32_e32 v219, v168, v219
	v_add_f32_e32 v219, v171, v219
	v_add_f32_e32 v219, v169, v219
	v_add_f32_e32 v219, v170, v219
	v_add_f32_e32 v219, v228, v219
	v_add_f32_e32 v219, v229, v219
	v_add_f32_e32 v219, v230, v219
	v_add_f32_e32 v219, v231, v219
	v_add_f32_e32 v219, v232, v219
	v_add_f32_e32 v219, v221, v219
	v_add_f32_e32 v219, v222, v219
	v_add_f32_e32 v219, v223, v219
	v_add_f32_e32 v219, v224, v219
	v_add_f32_e32 v219, v225, v219
	v_mfma_f32_32x32x16_bf16 v[64:79], v[240:243], v[98:101], v[64:79]
	s_cmp_ge_u32 s30, s29
	s_cselect_b64 s[22:23], -1, 0
	s_and_b64 vcc, exec, s[22:23]
	s_cbranch_vccnz .Lap_skipaddr
	v_add_co_u32_e32 v130, vcc, 0x48888000, v188
	s_nop 1
	v_addc_co_u32_e32 v131, vcc, 0, v189, vcc
	v_add_co_u32_e32 v134, vcc, 0x48888000, v186
	s_nop 1
	v_addc_co_u32_e32 v135, vcc, 0, v187, vcc
	v_add_co_u32_e32 v138, vcc, 0x48048000, v188
	s_nop 1
	v_addc_co_u32_e32 v139, vcc, 0, v189, vcc
	v_add_co_u32_e32 v142, vcc, 0x48048000, v186
	s_nop 1
	v_addc_co_u32_e32 v143, vcc, 0, v187, vcc
; #define SBAR() __builtin_amdgcn_sched_barrier(0)
; __device__ __forceinline__ void attn_body(const bf16_t* __restrict__ Qb, const bf16_t* __restrict__ Kh, const bf16_t* __restrict__ Vh,
;                                           bf16_t* __restrict__ Ob, const bf16_t* __restrict__ AGb, int seq, char* lds) {
;     ...
;     finishSM(pB0, pB1, alB, l_reg, pa0, pa1, pa2, pa3); SBAR();
;     if (j + 3 < NT) SLOAD(SE, (j + 3) * KVBLK); SBAR();
.Lap_skipaddr:
	v_add_f32_e32 v219, v226, v219
	v_add_f32_e32 v219, v227, v219
	v_add_f32_e32 v219, v235, v219
	v_add_f32_e32 v219, v233, v219
	v_add_f32_e32 v219, v234, v219
	v_add_f32_e32 v219, v236, v219
	v_mov_b32_e32 v220, v219
	v_cvt_pk_bf16_f32 v162, v162, v177
	v_cvt_pk_bf16_f32 v163, v163, v176
	v_cvt_pk_bf16_f32 v164, v164, v175
	v_cvt_pk_bf16_f32 v165, v165, v174
	v_cvt_pk_bf16_f32 v166, v166, v173
	v_cvt_pk_bf16_f32 v167, v167, v172
	v_cvt_pk_bf16_f32 v168, v168, v171
	v_cvt_pk_bf16_f32 v169, v169, v170
	v_cvt_pk_bf16_f32 v170, v228, v229
	v_cvt_pk_bf16_f32 v171, v230, v231
	v_cvt_pk_bf16_f32 v172, v232, v221
	v_cvt_pk_bf16_f32 v173, v222, v223
	v_cvt_pk_bf16_f32 v174, v224, v225
	v_cvt_pk_bf16_f32 v175, v226, v227
	v_cvt_pk_bf16_f32 v176, v235, v233
	v_cvt_pk_bf16_f32 v177, v234, v236
	ds_read_b64_tr_b16 v[186:187], v200 offset:0
	ds_read_b64_tr_b16 v[188:189], v200 offset:0x800
	ds_read_b64_tr_b16 v[222:223], v200 offset:0x1000
	ds_read_b64_tr_b16 v[224:225], v200 offset:0x1800
	ds_read_b64_tr_b16 v[226:227], v200 offset:0x2000
	ds_read_b64_tr_b16 v[228:229], v200 offset:0x2800
	ds_read_b64_tr_b16 v[230:231], v200 offset:0x3000
	ds_read_b64_tr_b16 v[232:233], v200 offset:0x3800
	s_nop 1
	v_permlane32_swap_b32_e32 v219, v220
	v_permlane32_swap_b32_e32 v162, v164
	v_permlane32_swap_b32_e32 v163, v165
	v_permlane32_swap_b32_e32 v166, v168
	v_permlane32_swap_b32_e32 v167, v169
	v_permlane32_swap_b32_e32 v170, v172
	v_permlane32_swap_b32_e32 v171, v173
	v_permlane32_swap_b32_e32 v174, v176
	v_permlane32_swap_b32_e32 v175, v177
	s_and_b64 vcc, exec, s[22:23]
	s_cbranch_vccnz .LBB0_205
	global_load_dwordx4 v[130:133], v[130:131], off
	s_nop 0
	global_load_dwordx4 v[134:137], v[134:135], off
	global_load_dwordx4 v[138:141], v[138:139], off
	s_nop 0
	global_load_dwordx4 v[142:145], v[142:143], off
; #define SBAR() __builtin_amdgcn_sched_barrier(0)
; #define SWRITE(b, i) do { *(bf16x8*)((char*)V_lds + (b) * SHM_V + vst0) = sr_[i].vs0;          \
;     *(bf16x8*)((char*)V_lds + (b) * SHM_V + vst1) = sr_[i].vs1; int kc = sc * 2;               \
;     *(bf16x8*)((char*)K_lds + (b) * SHM_K + KSWZ(sr, kc)) = sr_[i].ks0;                       \
;     *(bf16x8*)((char*)K_lds + (b) * SHM_K + KSWZ(32 + sr, kc)) = sr_[i].ks1; } while (0)
; #define SWAIT() asm volatile("s_waitcnt vmcnt(4)" ::: "memory")
; #define RESC(a) do { if (__any((a) < 1.f)) { if (hi == 0) al_l[r32] = (a); asm volatile("s_waitcnt lgkmcnt(0)" ::: "memory"); \
;     _Pragma("unroll") for (int d = 0; d < 4; ++d) _Pragma("unroll") for (int r = 0; r < 16; ++r) o[d][r] *= al_l[crow(r, hi)]; } } while (0)
; template <int D0> __device__ __forceinline__ void pv_one(f32x16& od, int vb, bf16x8 pa0, bf16x8 pa1, bf16x8 pa2, bf16x8 pa3) {
;   const s16x4 l0 = tr_read<v_rd_off(D0, 0, 0)>(vb), h0 = tr_read<v_rd_off(D0, 0, 1)>(vb), l1 = tr_read<v_rd_off(D0, 1, 0)>(vb), h1 = tr_read<v_rd_off(D0, 1, 1)>(vb);
;   const s16x4 l2 = tr_read<v_rd_off(D0, 2, 0)>(vb), h2 = tr_read<v_rd_off(D0, 2, 1)>(vb), l3 = tr_read<v_rd_off(D0, 3, 0)>(vb), h3 = tr_read<v_rd_off(D0, 3, 1)>(vb);
;   asm volatile("s_waitcnt lgkmcnt(0)" ::: "memory"); SBAR();
;     ...
;   od = __builtin_amdgcn_mfma_f32_32x32x16_bf16(pa0, PK(l0, h0), od, 0, 0, 0);
;   od = __builtin_amdgcn_mfma_f32_32x32x16_bf16(pa1, PK(l1, h1), od, 0, 0, 0);
;   od = __builtin_amdgcn_mfma_f32_32x32x16_bf16(pa2, PK(l2, h2), od, 0, 0, 0);
;   od = __builtin_amdgcn_mfma_f32_32x32x16_bf16(pa3, PK(l3, h3), od, 0, 0, 0);
;     ...
; }
; __device__ __forceinline__ void pv_d0(f32x16* o, int vb, bf16x8 pa0, bf16x8 pa1, bf16x8 pa2, bf16x8 pa3) {
;   pv_one<0>(o[0], vb, pa0, pa1, pa2, pa3); pv_one<1>(o[1], vb, pa0, pa1, pa2, pa3); pv_one<2>(o[2], vb, pa0, pa1, pa2, pa3); pv_one<3>(o[3], vb, pa0, pa1, pa2, pa3);
; }
; __device__ __forceinline__ void attn_body(const bf16_t* __restrict__ Qb, const bf16_t* __restrict__ Kh, const bf16_t* __restrict__ Vh,
;                                           bf16_t* __restrict__ Ob, const bf16_t* __restrict__ AGb, int seq, char* lds) {
;     ...
;     pv_d0(o, vb0 + (int)SHM_V, pa0, pa1, pa2, pa3); partialSM(pA0, pA1, m_reg, mnA, alA);
;     __syncthreads(); SWAIT(); SWRITE(1, SO);
;     RESC(alA); __syncthreads();
.LBB0_205:
	s_waitcnt lgkmcnt(0)
	s_nop 0
	v_mfma_f32_32x32x16_bf16 v[0:15], v[162:165], v[186:189], v[0:15]
	ds_read_b64_tr_b16 v[186:187], v200 offset:0x200
	ds_read_b64_tr_b16 v[188:189], v200 offset:0xa00
	v_mfma_f32_32x32x16_bf16 v[0:15], v[166:169], v[222:225], v[0:15]
	ds_read_b64_tr_b16 v[222:223], v200 offset:0x1200
	ds_read_b64_tr_b16 v[224:225], v200 offset:0x1a00
	v_mfma_f32_32x32x16_bf16 v[0:15], v[170:173], v[226:229], v[0:15]
	ds_read_b64_tr_b16 v[226:227], v200 offset:0x2200
	ds_read_b64_tr_b16 v[228:229], v200 offset:0x2a00
	v_mfma_f32_32x32x16_bf16 v[0:15], v[174:177], v[230:233], v[0:15]
	ds_read_b64_tr_b16 v[230:231], v200 offset:0x3200
	ds_read_b64_tr_b16 v[232:233], v200 offset:0x3a00
	s_waitcnt lgkmcnt(0)
	v_mfma_f32_32x32x16_bf16 v[48:63], v[162:165], v[186:189], v[48:63]
	ds_read_b64_tr_b16 v[186:187], v200 offset:0x400
	ds_read_b64_tr_b16 v[188:189], v200 offset:0xc00
	v_mfma_f32_32x32x16_bf16 v[48:63], v[166:169], v[222:225], v[48:63]
	ds_read_b64_tr_b16 v[222:223], v200 offset:0x1400
	ds_read_b64_tr_b16 v[224:225], v200 offset:0x1c00
	v_mfma_f32_32x32x16_bf16 v[48:63], v[170:173], v[226:229], v[48:63]
	ds_read_b64_tr_b16 v[226:227], v200 offset:0x2400
	ds_read_b64_tr_b16 v[228:229], v200 offset:0x2c00
	v_mfma_f32_32x32x16_bf16 v[48:63], v[174:177], v[230:233], v[48:63]
	ds_read_b64_tr_b16 v[230:231], v200 offset:0x3400
	ds_read_b64_tr_b16 v[232:233], v200 offset:0x3c00
	s_waitcnt lgkmcnt(0)
	v_mfma_f32_32x32x16_bf16 v[32:47], v[162:165], v[186:189], v[32:47]
	ds_read_b64_tr_b16 v[186:187], v200 offset:0x600
	ds_read_b64_tr_b16 v[188:189], v200 offset:0xe00
	v_mfma_f32_32x32x16_bf16 v[32:47], v[166:169], v[222:225], v[32:47]
	ds_read_b64_tr_b16 v[222:223], v200 offset:0x1600
	ds_read_b64_tr_b16 v[224:225], v200 offset:0x1e00
	v_mfma_f32_32x32x16_bf16 v[32:47], v[170:173], v[226:229], v[32:47]
	ds_read_b64_tr_b16 v[226:227], v200 offset:0x2600
	ds_read_b64_tr_b16 v[228:229], v200 offset:0x2e00
	v_mfma_f32_32x32x16_bf16 v[32:47], v[174:177], v[230:233], v[32:47]
	ds_read_b64_tr_b16 v[230:231], v200 offset:0x3600
	ds_read_b64_tr_b16 v[232:233], v200 offset:0x3e00
	s_waitcnt lgkmcnt(0)
	v_mfma_f32_32x32x16_bf16 v[16:31], v[162:165], v[186:189], v[16:31]
	v_max_f32_e32 v162, v81, v81
	v_max_f32_e32 v163, v80, v80
	v_max_f32_e32 v162, v163, v162
	v_max3_f32 v162, v162, v82, v83
	v_max3_f32 v162, v162, v84, v85
	v_max3_f32 v162, v162, v86, v87
	v_max3_f32 v162, v162, v88, v89
	v_max3_f32 v162, v162, v90, v91
	v_max3_f32 v162, v162, v92, v93
	v_mfma_f32_32x32x16_bf16 v[16:31], v[166:169], v[222:225], v[16:31]
	v_max3_f32 v162, v162, v94, v95
	v_max3_f32 v162, v162, v64, v65
	v_max3_f32 v162, v162, v66, v67
	v_max3_f32 v162, v162, v68, v69
	v_max3_f32 v162, v162, v70, v71
	v_max3_f32 v162, v162, v72, v73
	v_max3_f32 v162, v162, v74, v75
	v_max3_f32 v162, v162, v76, v77
	v_mfma_f32_32x32x16_bf16 v[16:31], v[170:173], v[226:229], v[16:31]
	v_max3_f32 v162, v162, v78, v79
	v_mov_b32_e32 v163, v162
	s_nop 1
	v_permlane32_swap_b32_e32 v162, v163
	v_max_f32_e32 v163, v163, v163
	v_max_f32_e32 v162, v162, v162
	v_max_f32_e32 v162, v162, v163
	v_sub_f32_e32 v163, v162, v218
	v_cmp_ge_f32_e32 vcc, s62, v163
	v_max_f32_e32 v163, v218, v218
	v_max_f32_e32 v163, v163, v162
	v_mfma_f32_32x32x16_bf16 v[16:31], v[174:177], v[230:233], v[16:31]
	v_sub_f32_e32 v162, v218, v163
	v_mul_f32_e32 v162, 0x3e0293ee, v162
	v_exp_f32_e32 v162, v162
	s_cmp_eq_u64 vcc, exec
	s_cselect_b64 s[0:1], -1, 0
	s_waitcnt lgkmcnt(0)
	s_barrier
	s_waitcnt vmcnt(4)
	v_cndmask_b32_e64 v162, v162, 1.0, s[0:1]
	v_cmp_gt_f32_e32 vcc, 1.0, v162
	s_waitcnt vmcnt(0)
	ds_write_b128 v204, v[146:149] offset:16384
	ds_write_b128 v205, v[150:153] offset:16384
	ds_write_b128 v202, v[154:157] offset:49152
	ds_write_b128 v203, v[158:161] offset:49152
	s_cbranch_vccz .LBB0_209
	s_and_saveexec_b64 s[24:25], s[4:5]
	ds_write_b32 v183, v162 offset:128
	s_or_b64 exec, exec, s[24:25]
	s_waitcnt lgkmcnt(0)
	v_add_u32_e32 v158, v181, v180
	ds_read_b128 v[146:149], v158 offset:224
	ds_read_b128 v[150:153], v158 offset:192
	ds_read_b128 v[154:157], v158 offset:160
	ds_read_b128 v[158:161], v158 offset:128
	s_waitcnt lgkmcnt(3)
	v_pk_mul_f32 v[12:13], v[12:13], v[146:147]
	s_waitcnt lgkmcnt(2)
	v_pk_mul_f32 v[8:9], v[8:9], v[150:151]
	s_waitcnt lgkmcnt(1)
	v_pk_mul_f32 v[4:5], v[4:5], v[154:155]
	v_pk_mul_f32 v[14:15], v[14:15], v[148:149]
	v_pk_mul_f32 v[10:11], v[10:11], v[152:153]
	v_pk_mul_f32 v[6:7], v[6:7], v[156:157]
	s_waitcnt lgkmcnt(0)
	v_pk_mul_f32 v[2:3], v[2:3], v[160:161]
	v_pk_mul_f32 v[0:1], v[0:1], v[158:159]
	v_pk_mul_f32 v[60:61], v[60:61], v[146:147]
	v_pk_mul_f32 v[56:57], v[56:57], v[150:151]
	v_pk_mul_f32 v[52:53], v[52:53], v[154:155]
	v_pk_mul_f32 v[62:63], v[62:63], v[148:149]
	v_pk_mul_f32 v[58:59], v[58:59], v[152:153]
	v_pk_mul_f32 v[54:55], v[54:55], v[156:157]
	v_pk_mul_f32 v[50:51], v[50:51], v[160:161]
	v_pk_mul_f32 v[48:49], v[48:49], v[158:159]
	v_pk_mul_f32 v[44:45], v[44:45], v[146:147]
	v_pk_mul_f32 v[40:41], v[40:41], v[150:151]
	v_pk_mul_f32 v[36:37], v[36:37], v[154:155]
	v_pk_mul_f32 v[46:47], v[46:47], v[148:149]
	v_pk_mul_f32 v[42:43], v[42:43], v[152:153]
	v_pk_mul_f32 v[38:39], v[38:39], v[156:157]
	v_pk_mul_f32 v[34:35], v[34:35], v[160:161]
	v_pk_mul_f32 v[32:33], v[32:33], v[158:159]
	v_pk_mul_f32 v[28:29], v[28:29], v[146:147]
	v_pk_mul_f32 v[24:25], v[24:25], v[150:151]
	v_pk_mul_f32 v[20:21], v[20:21], v[154:155]
	v_pk_mul_f32 v[30:31], v[30:31], v[148:149]
	v_pk_mul_f32 v[26:27], v[26:27], v[152:153]
	v_pk_mul_f32 v[22:23], v[22:23], v[156:157]
	v_pk_mul_f32 v[18:19], v[18:19], v[160:161]
	v_pk_mul_f32 v[16:17], v[16:17], v[158:159]
